# GEMM tiles: accumulator zero-init removed (first K-tile MFMAs take C=0), first loop iteration peeled
# speedup vs baseline: 1.0619x; 1.0048x over previous
.LBB0_40:
	s_ashr_i32 s2, s10, 31
	s_lshr_b32 s2, s2, 27
	s_add_i32 s2, s10, s2
	s_ashr_i32 s17, s2, 5
	s_andn2_b32 s2, s2, 31
	s_sub_i32 s2, s10, s2
	s_ashr_i32 s3, s2, 31
	s_lshr_b32 s3, s3, 29
	s_add_i32 s3, s2, s3
	s_ashr_i32 s3, s3, 3
	s_lshl_b32 s2, s2, 8
	s_lshl_b32 s14, s17, 11
	s_lshl_b32 s18, s3, 11
	s_add_i32 s2, s2, s14
	s_sub_i32 s14, s18, s2
	s_addk_i32 s14, 0x3f00
	s_lshl_b32 s15, s3, 8
	v_add_u32_e32 v2, s14, v180
	v_add_u32_e32 v15, s15, v180
	v_mad_i64_i32 v[48:49], s[2:3], v15, s5, v[164:165]
	v_mad_i64_i32 v[50:51], s[2:3], v2, s5, v[166:167]
	s_mov_b32 s2, 0x58000
	s_nop 0
	v_add_co_u32_e32 v52, vcc, s2, v50
	s_mov_b32 s3, 0xb0000
	s_nop 0
	v_addc_co_u32_e32 v53, vcc, 0, v51, vcc
	v_add_co_u32_e32 v54, vcc, s3, v50
	v_addc_co_u32_e32 v55, vcc, 0, v51, vcc
	v_add_co_u32_e32 v56, vcc, s2, v48
	s_mov_b32 s2, 0x108000
	s_nop 0
	v_addc_co_u32_e32 v57, vcc, 0, v49, vcc
	v_add_co_u32_e32 v58, vcc, s3, v48
	v_addc_co_u32_e32 v59, vcc, 0, v49, vcc
	v_add_co_u32_e32 v60, vcc, s2, v48
	v_addc_co_u32_e32 v61, vcc, 0, v49, vcc
	v_add_co_u32_e32 v62, vcc, s2, v50
	v_addc_co_u32_e32 v63, vcc, 0, v51, vcc
	s_mulk_i32 s17, 0x1800
	s_add_i32 s17, s18, s17
	v_mad_i64_i32 v[176:177], s[18:19], v15, s5, v[172:173]
	v_add_u32_e32 v15, s17, v190
	s_mov_b64 s[2:3], 0
	s_mov_b32 s16, 1
	v_mad_i64_i32 v[178:179], s[18:19], v15, s5, v[174:175]
	s_mov_b32 s4, 0x22c5000
	s_mov_b32 s12, 0x231d000
	s_mov_b32 s13, 0x2375000
	s_waitcnt lgkmcnt(0)
	v_lshrrev_b32_e32 v130, 6, v200
	v_and_b32_e32 v131, 63, v200
	v_readfirstlane_b32 s17, v130
	s_lshr_b32 s4, s17, 2
	s_lshl_b32 s4, s4, 7
	s_and_b32 s19, s17, 3
	s_lshl_b32 s19, s19, 4
	s_add_u32 s4, s4, s19
	s_add_u32 s19, s4, s14
	s_mul_i32 s19, s19, 5632
	s_add_u32 s2, s36, 0x518d800
	s_addc_u32 s3, s37, 0
	s_add_u32 s2, s2, s19
	s_addc_u32 s3, s3, 0
	s_lshl_b32 s4, s4, 7
	s_lshr_b32 s16, s17, 1
	s_lshl_b32 s16, s16, 6
	s_and_b32 s19, s17, 1
	s_lshl_b32 s19, s19, 4
	s_add_u32 s16, s16, s19
	v_readlane_b32 s13, v255, 30
	s_nop 3
	s_mul_i32 s13, s13, 0x580000
	s_add_u32 s12, s36, s13
	s_addc_u32 s13, s37, 0
	s_add_u32 s12, s12, 0x226d800
	s_addc_u32 s13, s13, 0
	s_add_u32 s19, s16, s15
	s_mul_i32 s19, s19, 5632
	s_add_u32 s12, s12, s19
	s_addc_u32 s13, s13, 0
	s_lshl_b32 s16, s16, 7
	s_add_u32 s16, s16, 0x10000
	v_lshrrev_b32_e32 v132, 3, v131
	v_and_b32_e32 v133, 7, v131
	v_lshrrev_b32_e32 v134, 4, v131
	v_xor_b32_e32 v133, v133, v134
	v_lshlrev_b32_e32 v133, 4, v133
	v_mul_u32_u24_e32 v134, 5632, v132
	v_or_b32_e32 v226, v134, v133
	v_add_u32_e32 v227, 45056, v226
	v_xor_b32_e32 v227, 64, v227
	v_add_u32_e32 v178, 0x58000, v226
	v_add_u32_e32 v179, 0x58000, v227
	v_mul_u32_u24_e32 v134, 5632, v132
	v_or_b32_e32 v228, v134, v133
	v_add_u32_e32 v214, 45056, v228
	v_xor_b32_e32 v214, 64, v214
	v_add_u32_e32 v203, 0x2c000, v228
	v_add_u32_e32 v204, 0x2c000, v214
	v_and_b32_e32 v132, 31, v131
	v_lshrrev_b32_e32 v133, 5, v131
	v_bfe_u32 v134, v132, 1, 3
	v_and_b32_e32 v135, 1, v134
	v_xor_b32_e32 v133, v133, v135
	v_lshlrev_b32_e32 v133, 4, v133
	v_lshl_add_u32 v133, v132, 7, v133
	v_and_b32_e32 v134, 6, v134
	s_lshr_b32 s19, s17, 2
	s_lshl_b32 s19, s19, 14
	v_xor_b32_e32 v135, 0, v134
	v_lshl_add_u32 v135, v135, 4, v133
	v_add_u32_e32 v246, s19, v135
	v_xor_b32_e32 v135, 2, v134
	v_lshl_add_u32 v135, v135, 4, v133
	v_add_u32_e32 v247, s19, v135
	v_xor_b32_e32 v135, 4, v134
	v_lshl_add_u32 v135, v135, 4, v133
	v_add_u32_e32 v248, s19, v135
	v_xor_b32_e32 v135, 6, v134
	v_lshl_add_u32 v135, v135, 4, v133
	v_add_u32_e32 v249, s19, v135
	s_and_b32 s19, s17, 3
	s_lshl_b32 s19, s19, 13
	s_add_u32 s19, s19, 0x10000
	v_xor_b32_e32 v135, 0, v134
	v_lshl_add_u32 v135, v135, 4, v133
	v_add_u32_e32 v250, s19, v135
	v_xor_b32_e32 v135, 2, v134
	v_lshl_add_u32 v135, v135, 4, v133
	v_add_u32_e32 v251, s19, v135
	v_xor_b32_e32 v135, 4, v134
	v_lshl_add_u32 v135, v135, 4, v133
	v_add_u32_e32 v252, s19, v135
	v_xor_b32_e32 v135, 6, v134
	v_lshl_add_u32 v135, v135, 4, v133
	v_add_u32_e32 v233, s19, v135
	s_add_u32 m0, s16, 0x0
	s_nop 0
	global_load_lds_dwordx4 v228, s[12:13]
	s_add_u32 m0, s16, 0x400
	s_nop 0
	global_load_lds_dwordx4 v214, s[12:13]
	s_add_u32 m0, s4, 0x0
	s_nop 0
	global_load_lds_dwordx4 v226, s[2:3]
	s_add_u32 m0, s4, 0x400
	s_nop 0
	global_load_lds_dwordx4 v227, s[2:3]
	s_add_u32 m0, s16, 0x1000
	s_nop 0
	global_load_lds_dwordx4 v203, s[12:13]
	s_add_u32 m0, s16, 0x1400
	s_nop 0
	global_load_lds_dwordx4 v204, s[12:13]
	s_add_u32 m0, s4, 0x2000
	s_nop 0
	global_load_lds_dwordx4 v178, s[2:3]
	s_add_u32 m0, s4, 0x2400
	s_nop 0
	global_load_lds_dwordx4 v179, s[2:3]
	v_readfirstlane_b32 s19, v200
	s_lshr_b32 s19, s19, 8
	s_cmp_lg_u32 s19, 0
	s_cbranch_scc0 .Lgdn_nolag
	s_barrier
.Lgdn_nolag:
	s_waitcnt vmcnt(4)
	s_barrier
	s_add_u32 s12, s12, 0x80
	s_addc_u32 s13, s13, 0
	s_add_u32 m0, s16, 0x8000
	s_nop 0
	global_load_lds_dwordx4 v228, s[12:13]
	s_add_u32 m0, s16, 0x8400
	s_nop 0
	global_load_lds_dwordx4 v214, s[12:13]
	s_add_u32 s2, s2, 0x80
	s_addc_u32 s3, s3, 0
	s_add_u32 m0, s4, 0x8000
	s_nop 0
	global_load_lds_dwordx4 v226, s[2:3]
	s_add_u32 m0, s4, 0x8400
	s_nop 0
	global_load_lds_dwordx4 v227, s[2:3]
	s_add_u32 m0, s16, 0x9000
	s_nop 0
	global_load_lds_dwordx4 v203, s[12:13]
	s_add_u32 m0, s16, 0x9400
	s_nop 0
	global_load_lds_dwordx4 v204, s[12:13]
	s_waitcnt vmcnt(6)
	s_barrier
	ds_read_b128 v[192:195], v250
	ds_read_b128 v[196:199], v251
	ds_read_b128 v[208:211], v252
	ds_read_b128 v[218:221], v233
	ds_read_b128 v[130:133], v246 offset:0
	ds_read_b128 v[134:137], v247 offset:0
	ds_read_b128 v[138:141], v248 offset:0
	ds_read_b128 v[142:145], v249 offset:0
	ds_read_b128 v[146:149], v246 offset:4096
	ds_read_b128 v[150:153], v247 offset:4096
	ds_read_b128 v[154:157], v248 offset:4096
	ds_read_b128 v[158:161], v249 offset:4096
	s_add_u32 m0, s4, 0xa000
	s_nop 0
	global_load_lds_dwordx4 v178, s[2:3]
	s_add_u32 m0, s4, 0xa400
	s_nop 0
	global_load_lds_dwordx4 v179, s[2:3]
	s_waitcnt lgkmcnt(8)
	s_barrier
	s_waitcnt lgkmcnt(0)
	s_setprio 1
	v_mfma_f32_32x32x16_bf16 v[114:129], v[192:195], v[130:133], 0
	v_mfma_f32_32x32x16_bf16 v[82:97], v[192:195], v[146:149], 0
	v_mfma_f32_32x32x16_bf16 v[114:129], v[196:199], v[134:137], v[114:129]
	v_mfma_f32_32x32x16_bf16 v[82:97], v[196:199], v[150:153], v[82:97]
	v_mfma_f32_32x32x16_bf16 v[114:129], v[208:211], v[138:141], v[114:129]
	v_mfma_f32_32x32x16_bf16 v[82:97], v[208:211], v[154:157], v[82:97]
	v_mfma_f32_32x32x16_bf16 v[114:129], v[218:221], v[142:145], v[114:129]
	v_mfma_f32_32x32x16_bf16 v[82:97], v[218:221], v[158:161], v[82:97]
	s_setprio 0
	s_barrier
	ds_read_b128 v[222:225], v250 offset:4096
	ds_read_b128 v[234:237], v251 offset:4096
	ds_read_b128 v[238:241], v252 offset:4096
	ds_read_b128 v[242:245], v233 offset:4096
	s_add_u32 s12, s12, 0x80
	s_addc_u32 s13, s13, 0
	s_add_u32 m0, s16, 0x0
	s_nop 0
	global_load_lds_dwordx4 v228, s[12:13]
	s_add_u32 m0, s16, 0x400
	s_nop 0
	global_load_lds_dwordx4 v214, s[12:13]
	s_barrier
	s_waitcnt lgkmcnt(0)
	s_setprio 1
	v_mfma_f32_32x32x16_bf16 v[98:113], v[222:225], v[130:133], 0
	v_mfma_f32_32x32x16_bf16 v[66:81], v[222:225], v[146:149], 0
	v_mfma_f32_32x32x16_bf16 v[98:113], v[234:237], v[134:137], v[98:113]
	v_mfma_f32_32x32x16_bf16 v[66:81], v[234:237], v[150:153], v[66:81]
	v_mfma_f32_32x32x16_bf16 v[98:113], v[238:241], v[138:141], v[98:113]
	v_mfma_f32_32x32x16_bf16 v[66:81], v[238:241], v[154:157], v[66:81]
	v_mfma_f32_32x32x16_bf16 v[98:113], v[242:245], v[142:145], v[98:113]
	v_mfma_f32_32x32x16_bf16 v[66:81], v[242:245], v[158:161], v[66:81]
	s_setprio 0
	s_barrier
	ds_read_b128 v[130:133], v246 offset:8192
	ds_read_b128 v[134:137], v247 offset:8192
	ds_read_b128 v[138:141], v248 offset:8192
	ds_read_b128 v[142:145], v249 offset:8192
	ds_read_b128 v[146:149], v246 offset:12288
	ds_read_b128 v[150:153], v247 offset:12288
	ds_read_b128 v[154:157], v248 offset:12288
	ds_read_b128 v[158:161], v249 offset:12288
	s_add_u32 s2, s2, 0x80
	s_addc_u32 s3, s3, 0
	s_add_u32 m0, s4, 0x0
	s_nop 0
	global_load_lds_dwordx4 v226, s[2:3]
	s_add_u32 m0, s4, 0x400
	s_nop 0
	global_load_lds_dwordx4 v227, s[2:3]
	s_barrier
	s_waitcnt lgkmcnt(0)
	s_setprio 1
	v_mfma_f32_32x32x16_bf16 v[50:65], v[192:195], v[130:133], 0
	v_mfma_f32_32x32x16_bf16 v[18:33], v[192:195], v[146:149], 0
	v_mfma_f32_32x32x16_bf16 v[50:65], v[196:199], v[134:137], v[50:65]
	v_mfma_f32_32x32x16_bf16 v[18:33], v[196:199], v[150:153], v[18:33]
	v_mfma_f32_32x32x16_bf16 v[50:65], v[208:211], v[138:141], v[50:65]
	v_mfma_f32_32x32x16_bf16 v[18:33], v[208:211], v[154:157], v[18:33]
	v_mfma_f32_32x32x16_bf16 v[50:65], v[218:221], v[142:145], v[50:65]
	v_mfma_f32_32x32x16_bf16 v[18:33], v[218:221], v[158:161], v[18:33]
	s_setprio 0
	s_barrier
	s_add_u32 m0, s16, 0x1000
	s_nop 0
	global_load_lds_dwordx4 v203, s[12:13]
	s_add_u32 m0, s16, 0x1400
	s_nop 0
	global_load_lds_dwordx4 v204, s[12:13]
	s_waitcnt vmcnt(6)
	s_barrier
	s_setprio 1
	v_mfma_f32_32x32x16_bf16 v[34:49], v[222:225], v[130:133], 0
	v_mfma_f32_32x32x16_bf16 v[2:17], v[222:225], v[146:149], 0
	v_mfma_f32_32x32x16_bf16 v[34:49], v[234:237], v[134:137], v[34:49]
	v_mfma_f32_32x32x16_bf16 v[2:17], v[234:237], v[150:153], v[2:17]
	v_mfma_f32_32x32x16_bf16 v[34:49], v[238:241], v[138:141], v[34:49]
	v_mfma_f32_32x32x16_bf16 v[2:17], v[238:241], v[154:157], v[2:17]
	v_mfma_f32_32x32x16_bf16 v[34:49], v[242:245], v[142:145], v[34:49]
	v_mfma_f32_32x32x16_bf16 v[2:17], v[242:245], v[158:161], v[2:17]
	s_setprio 0
	s_barrier
	ds_read_b128 v[192:195], v250 offset:32768
	ds_read_b128 v[196:199], v251 offset:32768
	ds_read_b128 v[208:211], v252 offset:32768
	ds_read_b128 v[218:221], v233 offset:32768
	ds_read_b128 v[130:133], v246 offset:32768
	ds_read_b128 v[134:137], v247 offset:32768
	ds_read_b128 v[138:141], v248 offset:32768
	ds_read_b128 v[142:145], v249 offset:32768
	ds_read_b128 v[146:149], v246 offset:36864
	ds_read_b128 v[150:153], v247 offset:36864
	ds_read_b128 v[154:157], v248 offset:36864
	ds_read_b128 v[158:161], v249 offset:36864
	s_add_u32 m0, s4, 0x2000
	s_nop 0
	global_load_lds_dwordx4 v178, s[2:3]
	s_add_u32 m0, s4, 0x2400
	s_nop 0
	global_load_lds_dwordx4 v179, s[2:3]
	s_waitcnt lgkmcnt(8)
	s_barrier
	s_waitcnt lgkmcnt(0)
	s_setprio 1
	v_mfma_f32_32x32x16_bf16 v[114:129], v[192:195], v[130:133], v[114:129]
	v_mfma_f32_32x32x16_bf16 v[82:97], v[192:195], v[146:149], v[82:97]
	v_mfma_f32_32x32x16_bf16 v[114:129], v[196:199], v[134:137], v[114:129]
	v_mfma_f32_32x32x16_bf16 v[82:97], v[196:199], v[150:153], v[82:97]
	v_mfma_f32_32x32x16_bf16 v[114:129], v[208:211], v[138:141], v[114:129]
	v_mfma_f32_32x32x16_bf16 v[82:97], v[208:211], v[154:157], v[82:97]
	v_mfma_f32_32x32x16_bf16 v[114:129], v[218:221], v[142:145], v[114:129]
	v_mfma_f32_32x32x16_bf16 v[82:97], v[218:221], v[158:161], v[82:97]
	s_setprio 0
	s_barrier
	ds_read_b128 v[222:225], v250 offset:36864
	ds_read_b128 v[234:237], v251 offset:36864
	ds_read_b128 v[238:241], v252 offset:36864
	ds_read_b128 v[242:245], v233 offset:36864
	s_add_u32 s12, s12, 0x80
	s_addc_u32 s13, s13, 0
	s_add_u32 m0, s16, 0x8000
	s_nop 0
	global_load_lds_dwordx4 v228, s[12:13]
	s_add_u32 m0, s16, 0x8400
	s_nop 0
	global_load_lds_dwordx4 v214, s[12:13]
	s_barrier
	s_waitcnt lgkmcnt(0)
	s_setprio 1
	v_mfma_f32_32x32x16_bf16 v[98:113], v[222:225], v[130:133], v[98:113]
	v_mfma_f32_32x32x16_bf16 v[66:81], v[222:225], v[146:149], v[66:81]
	v_mfma_f32_32x32x16_bf16 v[98:113], v[234:237], v[134:137], v[98:113]
	v_mfma_f32_32x32x16_bf16 v[66:81], v[234:237], v[150:153], v[66:81]
	v_mfma_f32_32x32x16_bf16 v[98:113], v[238:241], v[138:141], v[98:113]
	v_mfma_f32_32x32x16_bf16 v[66:81], v[238:241], v[154:157], v[66:81]
	v_mfma_f32_32x32x16_bf16 v[98:113], v[242:245], v[142:145], v[98:113]
	v_mfma_f32_32x32x16_bf16 v[66:81], v[242:245], v[158:161], v[66:81]
	s_setprio 0
	s_barrier
	ds_read_b128 v[130:133], v246 offset:40960
	ds_read_b128 v[134:137], v247 offset:40960
	ds_read_b128 v[138:141], v248 offset:40960
	ds_read_b128 v[142:145], v249 offset:40960
	ds_read_b128 v[146:149], v246 offset:45056
	ds_read_b128 v[150:153], v247 offset:45056
	ds_read_b128 v[154:157], v248 offset:45056
	ds_read_b128 v[158:161], v249 offset:45056
	s_add_u32 s2, s2, 0x80
	s_addc_u32 s3, s3, 0
	s_add_u32 m0, s4, 0x8000
	s_nop 0
	global_load_lds_dwordx4 v226, s[2:3]
	s_add_u32 m0, s4, 0x8400
	s_nop 0
	global_load_lds_dwordx4 v227, s[2:3]
	s_barrier
	s_waitcnt lgkmcnt(0)
	s_setprio 1
	v_mfma_f32_32x32x16_bf16 v[50:65], v[192:195], v[130:133], v[50:65]
	v_mfma_f32_32x32x16_bf16 v[18:33], v[192:195], v[146:149], v[18:33]
	v_mfma_f32_32x32x16_bf16 v[50:65], v[196:199], v[134:137], v[50:65]
	v_mfma_f32_32x32x16_bf16 v[18:33], v[196:199], v[150:153], v[18:33]
	v_mfma_f32_32x32x16_bf16 v[50:65], v[208:211], v[138:141], v[50:65]
	v_mfma_f32_32x32x16_bf16 v[18:33], v[208:211], v[154:157], v[18:33]
	v_mfma_f32_32x32x16_bf16 v[50:65], v[218:221], v[142:145], v[50:65]
	v_mfma_f32_32x32x16_bf16 v[18:33], v[218:221], v[158:161], v[18:33]
	s_setprio 0
	s_barrier
	s_add_u32 m0, s16, 0x9000
	s_nop 0
	global_load_lds_dwordx4 v203, s[12:13]
	s_add_u32 m0, s16, 0x9400
	s_nop 0
	global_load_lds_dwordx4 v204, s[12:13]
	s_waitcnt vmcnt(6)
	s_barrier
	s_setprio 1
	v_mfma_f32_32x32x16_bf16 v[34:49], v[222:225], v[130:133], v[34:49]
	v_mfma_f32_32x32x16_bf16 v[2:17], v[222:225], v[146:149], v[2:17]
	v_mfma_f32_32x32x16_bf16 v[34:49], v[234:237], v[134:137], v[34:49]
	v_mfma_f32_32x32x16_bf16 v[2:17], v[234:237], v[150:153], v[2:17]
	v_mfma_f32_32x32x16_bf16 v[34:49], v[238:241], v[138:141], v[34:49]
	v_mfma_f32_32x32x16_bf16 v[2:17], v[238:241], v[154:157], v[2:17]
	v_mfma_f32_32x32x16_bf16 v[34:49], v[242:245], v[142:145], v[34:49]
	v_mfma_f32_32x32x16_bf16 v[2:17], v[242:245], v[158:161], v[2:17]
	s_setprio 0
	s_barrier
	s_mov_b32 s17, 2

.LBB0_53:
	s_mul_hi_i32 s2, s10, 0x2e8ba2e9
	s_lshr_b32 s3, s2, 31
	s_ashr_i32 s2, s2, 5
	s_add_i32 s17, s2, s3
	s_lshl_b32 s2, s17, 3
	s_sub_i32 s3, s0, s2
	s_min_i32 s3, s3, 8
	s_abs_i32 s14, s3
	v_cvt_f32_u32_e32 v2, s14
	s_sub_i32 s19, 0, s14
	s_mul_i32 s15, s17, 0xffffff50
	s_add_i32 s15, s15, s10
	v_rcp_iflag_f32_e32 v2, v2
	s_abs_i32 s16, s15
	s_xor_b32 s18, s15, s3
	s_ashr_i32 s18, s18, 31
	v_mul_f32_e32 v2, 0x4f7ffffe, v2
	v_cvt_u32_f32_e32 v2, v2
	s_mulk_i32 s17, 0xa8
	s_mov_b32 s4, 0x308d000
	s_mov_b32 s6, 0x30ad000
	v_readfirstlane_b32 s22, v2
	s_mul_i32 s19, s19, s22
	s_mul_hi_u32 s19, s22, s19
	s_add_i32 s22, s22, s19
	s_mul_hi_u32 s19, s16, s22
	s_mul_i32 s22, s19, s14
	s_sub_i32 s16, s16, s22
	s_add_i32 s23, s19, 1
	s_sub_i32 s22, s16, s14
	s_cmp_ge_u32 s16, s14
	s_cselect_b32 s19, s23, s19
	s_cselect_b32 s16, s22, s16
	s_add_i32 s22, s19, 1
	s_cmp_ge_u32 s16, s14
	s_cselect_b32 s14, s22, s19
	s_xor_b32 s14, s14, s18
	s_sub_i32 s16, s14, s18
	s_mul_i32 s18, s16, s3
	s_add_i32 s15, s15, s2
	s_sub_i32 s2, s15, s18
	s_lshl_b32 s14, s2, 8
	v_add_u32_e32 v2, s14, v164
	v_ashrrev_i32_e32 v3, 31, v2
	v_lshlrev_b64 v[2:3], 11, v[2:3]
	s_lshl_b32 s15, s16, 8
	v_lshl_add_u64 v[52:53], v[168:169], 0, v[2:3]
	s_mov_b32 s2, 0x20000
	v_add_u32_e32 v4, s15, v164
	v_add_co_u32_e32 v54, vcc, s2, v52
	v_ashrrev_i32_e32 v5, 31, v4
	s_nop 0
	v_addc_co_u32_e32 v55, vcc, 0, v53, vcc
	s_mov_b32 s3, 0x40000
	v_lshlrev_b64 v[48:49], 11, v[4:5]
	v_add_co_u32_e32 v56, vcc, s3, v52
	v_lshl_add_u64 v[50:51], v[166:167], 0, v[48:49]
	s_nop 0
	v_addc_co_u32_e32 v57, vcc, 0, v53, vcc
	v_add_co_u32_e32 v58, vcc, s2, v50
	s_mov_b32 s2, 0x60000
	s_nop 0
	v_addc_co_u32_e32 v59, vcc, 0, v51, vcc
	v_add_co_u32_e32 v60, vcc, s3, v50
	v_addc_co_u32_e32 v61, vcc, 0, v51, vcc
	v_add_co_u32_e32 v62, vcc, s2, v50
	v_addc_co_u32_e32 v63, vcc, 0, v51, vcc
	v_add_co_u32_e32 v64, vcc, s2, v52
	v_addc_co_u32_e32 v65, vcc, 0, v53, vcc
	s_sub_i32 s18, s10, s18
	s_sub_i32 s17, s18, s17
	s_lshl_b32 s18, s17, 8
	s_ashr_i32 s19, s18, 31
	v_lshl_add_u64 v[178:179], v[174:175], 0, v[48:49]
	v_lshl_add_u64 v[48:49], v[164:165], 0, s[18:19]
	v_lshlrev_b64 v[48:49], 11, v[48:49]
	s_mov_b32 s16, 1
	s_mov_b64 s[2:3], 0
	v_lshl_add_u64 v[180:181], v[176:177], 0, v[48:49]
	s_mov_b32 s7, 0x30cd000
	s_waitcnt lgkmcnt(0)
	v_lshrrev_b32_e32 v130, 6, v200
	v_and_b32_e32 v131, 63, v200
	v_readfirstlane_b32 s17, v130
	s_lshr_b32 s4, s17, 2
	s_lshl_b32 s4, s4, 7
	s_and_b32 s19, s17, 3
	s_lshl_b32 s19, s19, 4
	s_add_u32 s4, s4, s19
	s_add_u32 s19, s4, s14
	s_mul_i32 s19, s19, 2048
	s_add_u32 s2, s36, 0x308d800
	s_addc_u32 s3, s37, 0
	s_add_u32 s2, s2, s19
	s_addc_u32 s3, s3, 0
	s_lshl_b32 s4, s4, 7
	s_lshr_b32 s16, s17, 1
	s_lshl_b32 s16, s16, 6
	s_and_b32 s19, s17, 1
	s_lshl_b32 s19, s19, 4
	s_add_u32 s16, s16, s19
	v_readlane_b32 s7, v255, 30
	s_nop 3
	s_mul_i32 s7, s7, 0xb00000
	s_add_u32 s6, s36, s7
	s_addc_u32 s7, s37, 0
	s_add_u32 s6, s6, 0xc6d800
	s_addc_u32 s7, s7, 0
	s_add_u32 s19, s16, s15
	s_mul_i32 s19, s19, 2048
	s_add_u32 s6, s6, s19
	s_addc_u32 s7, s7, 0
	s_lshl_b32 s16, s16, 7
	s_add_u32 s16, s16, 0x10000
	v_lshrrev_b32_e32 v132, 3, v131
	v_and_b32_e32 v133, 7, v131
	v_lshrrev_b32_e32 v134, 4, v131
	v_xor_b32_e32 v133, v133, v134
	v_lshlrev_b32_e32 v133, 4, v133
	v_mul_u32_u24_e32 v134, 2048, v132
	v_or_b32_e32 v226, v134, v133
	v_add_u32_e32 v227, 16384, v226
	v_xor_b32_e32 v227, 64, v227
	v_add_u32_e32 v178, 0x20000, v226
	v_add_u32_e32 v179, 0x20000, v227
	v_mul_u32_u24_e32 v134, 2048, v132
	v_or_b32_e32 v228, v134, v133
	v_add_u32_e32 v214, 16384, v228
	v_xor_b32_e32 v214, 64, v214
	v_add_u32_e32 v203, 0x10000, v228
	v_add_u32_e32 v204, 0x10000, v214
	v_and_b32_e32 v132, 31, v131
	v_lshrrev_b32_e32 v133, 5, v131
	v_bfe_u32 v134, v132, 1, 3
	v_and_b32_e32 v135, 1, v134
	v_xor_b32_e32 v133, v133, v135
	v_lshlrev_b32_e32 v133, 4, v133
	v_lshl_add_u32 v133, v132, 7, v133
	v_and_b32_e32 v134, 6, v134
	s_lshr_b32 s19, s17, 2
	s_lshl_b32 s19, s19, 14
	v_xor_b32_e32 v135, 0, v134
	v_lshl_add_u32 v135, v135, 4, v133
	v_add_u32_e32 v246, s19, v135
	v_xor_b32_e32 v135, 2, v134
	v_lshl_add_u32 v135, v135, 4, v133
	v_add_u32_e32 v247, s19, v135
	v_xor_b32_e32 v135, 4, v134
	v_lshl_add_u32 v135, v135, 4, v133
	v_add_u32_e32 v248, s19, v135
	v_xor_b32_e32 v135, 6, v134
	v_lshl_add_u32 v135, v135, 4, v133
	v_add_u32_e32 v249, s19, v135
	s_and_b32 s19, s17, 3
	s_lshl_b32 s19, s19, 13
	s_add_u32 s19, s19, 0x10000
	v_xor_b32_e32 v135, 0, v134
	v_lshl_add_u32 v135, v135, 4, v133
	v_add_u32_e32 v250, s19, v135
	v_xor_b32_e32 v135, 2, v134
	v_lshl_add_u32 v135, v135, 4, v133
	v_add_u32_e32 v251, s19, v135
	v_xor_b32_e32 v135, 4, v134
	v_lshl_add_u32 v135, v135, 4, v133
	v_add_u32_e32 v252, s19, v135
	v_xor_b32_e32 v135, 6, v134
	v_lshl_add_u32 v135, v135, 4, v133
	v_add_u32_e32 v233, s19, v135
	s_add_u32 m0, s16, 0x0
	s_nop 0
	global_load_lds_dwordx4 v228, s[6:7]
	s_add_u32 m0, s16, 0x400
	s_nop 0
	global_load_lds_dwordx4 v214, s[6:7]
	s_add_u32 m0, s4, 0x0
	s_nop 0
	global_load_lds_dwordx4 v226, s[2:3]
	s_add_u32 m0, s4, 0x400
	s_nop 0
	global_load_lds_dwordx4 v227, s[2:3]
	s_add_u32 m0, s16, 0x1000
	s_nop 0
	global_load_lds_dwordx4 v203, s[6:7]
	s_add_u32 m0, s16, 0x1400
	s_nop 0
	global_load_lds_dwordx4 v204, s[6:7]
	s_add_u32 m0, s4, 0x2000
	s_nop 0
	global_load_lds_dwordx4 v178, s[2:3]
	s_add_u32 m0, s4, 0x2400
	s_nop 0
	global_load_lds_dwordx4 v179, s[2:3]
	v_readfirstlane_b32 s19, v200
	s_lshr_b32 s19, s19, 8
	s_cmp_lg_u32 s19, 0
	s_cbranch_scc0 .Lggu_nolag
	s_barrier
.Lggu_nolag:
	s_waitcnt vmcnt(4)
	s_barrier
	s_add_u32 s6, s6, 0x80
	s_addc_u32 s7, s7, 0
	s_add_u32 m0, s16, 0x8000
	s_nop 0
	global_load_lds_dwordx4 v228, s[6:7]
	s_add_u32 m0, s16, 0x8400
	s_nop 0
	global_load_lds_dwordx4 v214, s[6:7]
	s_add_u32 s2, s2, 0x80
	s_addc_u32 s3, s3, 0
	s_add_u32 m0, s4, 0x8000
	s_nop 0
	global_load_lds_dwordx4 v226, s[2:3]
	s_add_u32 m0, s4, 0x8400
	s_nop 0
	global_load_lds_dwordx4 v227, s[2:3]
	s_add_u32 m0, s16, 0x9000
	s_nop 0
	global_load_lds_dwordx4 v203, s[6:7]
	s_add_u32 m0, s16, 0x9400
	s_nop 0
	global_load_lds_dwordx4 v204, s[6:7]
	s_waitcnt vmcnt(6)
	s_barrier
	ds_read_b128 v[192:195], v250
	ds_read_b128 v[196:199], v251
	ds_read_b128 v[208:211], v252
	ds_read_b128 v[218:221], v233
	ds_read_b128 v[130:133], v246 offset:0
	ds_read_b128 v[134:137], v247 offset:0
	ds_read_b128 v[138:141], v248 offset:0
	ds_read_b128 v[142:145], v249 offset:0
	ds_read_b128 v[146:149], v246 offset:4096
	ds_read_b128 v[150:153], v247 offset:4096
	ds_read_b128 v[154:157], v248 offset:4096
	ds_read_b128 v[158:161], v249 offset:4096
	s_add_u32 m0, s4, 0xa000
	s_nop 0
	global_load_lds_dwordx4 v178, s[2:3]
	s_add_u32 m0, s4, 0xa400
	s_nop 0
	global_load_lds_dwordx4 v179, s[2:3]
	s_waitcnt lgkmcnt(8)
	s_barrier
	s_waitcnt lgkmcnt(0)
	s_setprio 1
	v_mfma_f32_32x32x16_bf16 v[114:129], v[192:195], v[130:133], 0
	v_mfma_f32_32x32x16_bf16 v[82:97], v[192:195], v[146:149], 0
	v_mfma_f32_32x32x16_bf16 v[114:129], v[196:199], v[134:137], v[114:129]
	v_mfma_f32_32x32x16_bf16 v[82:97], v[196:199], v[150:153], v[82:97]
	v_mfma_f32_32x32x16_bf16 v[114:129], v[208:211], v[138:141], v[114:129]
	v_mfma_f32_32x32x16_bf16 v[82:97], v[208:211], v[154:157], v[82:97]
	v_mfma_f32_32x32x16_bf16 v[114:129], v[218:221], v[142:145], v[114:129]
	v_mfma_f32_32x32x16_bf16 v[82:97], v[218:221], v[158:161], v[82:97]
	s_setprio 0
	s_barrier
	ds_read_b128 v[222:225], v250 offset:4096
	ds_read_b128 v[234:237], v251 offset:4096
	ds_read_b128 v[238:241], v252 offset:4096
	ds_read_b128 v[242:245], v233 offset:4096
	s_add_u32 s6, s6, 0x80
	s_addc_u32 s7, s7, 0
	s_add_u32 m0, s16, 0x0
	s_nop 0
	global_load_lds_dwordx4 v228, s[6:7]
	s_add_u32 m0, s16, 0x400
	s_nop 0
	global_load_lds_dwordx4 v214, s[6:7]
	s_barrier
	s_waitcnt lgkmcnt(0)
	s_setprio 1
	v_mfma_f32_32x32x16_bf16 v[98:113], v[222:225], v[130:133], 0
	v_mfma_f32_32x32x16_bf16 v[66:81], v[222:225], v[146:149], 0
	v_mfma_f32_32x32x16_bf16 v[98:113], v[234:237], v[134:137], v[98:113]
	v_mfma_f32_32x32x16_bf16 v[66:81], v[234:237], v[150:153], v[66:81]
	v_mfma_f32_32x32x16_bf16 v[98:113], v[238:241], v[138:141], v[98:113]
	v_mfma_f32_32x32x16_bf16 v[66:81], v[238:241], v[154:157], v[66:81]
	v_mfma_f32_32x32x16_bf16 v[98:113], v[242:245], v[142:145], v[98:113]
	v_mfma_f32_32x32x16_bf16 v[66:81], v[242:245], v[158:161], v[66:81]
	s_setprio 0
	s_barrier
	ds_read_b128 v[130:133], v246 offset:8192
	ds_read_b128 v[134:137], v247 offset:8192
	ds_read_b128 v[138:141], v248 offset:8192
	ds_read_b128 v[142:145], v249 offset:8192
	ds_read_b128 v[146:149], v246 offset:12288
	ds_read_b128 v[150:153], v247 offset:12288
	ds_read_b128 v[154:157], v248 offset:12288
	ds_read_b128 v[158:161], v249 offset:12288
	s_add_u32 s2, s2, 0x80
	s_addc_u32 s3, s3, 0
	s_add_u32 m0, s4, 0x0
	s_nop 0
	global_load_lds_dwordx4 v226, s[2:3]
	s_add_u32 m0, s4, 0x400
	s_nop 0
	global_load_lds_dwordx4 v227, s[2:3]
	s_barrier
	s_waitcnt lgkmcnt(0)
	s_setprio 1
	v_mfma_f32_32x32x16_bf16 v[50:65], v[192:195], v[130:133], 0
	v_mfma_f32_32x32x16_bf16 v[18:33], v[192:195], v[146:149], 0
	v_mfma_f32_32x32x16_bf16 v[50:65], v[196:199], v[134:137], v[50:65]
	v_mfma_f32_32x32x16_bf16 v[18:33], v[196:199], v[150:153], v[18:33]
	v_mfma_f32_32x32x16_bf16 v[50:65], v[208:211], v[138:141], v[50:65]
	v_mfma_f32_32x32x16_bf16 v[18:33], v[208:211], v[154:157], v[18:33]
	v_mfma_f32_32x32x16_bf16 v[50:65], v[218:221], v[142:145], v[50:65]
	v_mfma_f32_32x32x16_bf16 v[18:33], v[218:221], v[158:161], v[18:33]
	s_setprio 0
	s_barrier
	s_add_u32 m0, s16, 0x1000
	s_nop 0
	global_load_lds_dwordx4 v203, s[6:7]
	s_add_u32 m0, s16, 0x1400
	s_nop 0
	global_load_lds_dwordx4 v204, s[6:7]
	s_waitcnt vmcnt(6)
	s_barrier
	s_setprio 1
	v_mfma_f32_32x32x16_bf16 v[34:49], v[222:225], v[130:133], 0
	v_mfma_f32_32x32x16_bf16 v[2:17], v[222:225], v[146:149], 0
	v_mfma_f32_32x32x16_bf16 v[34:49], v[234:237], v[134:137], v[34:49]
	v_mfma_f32_32x32x16_bf16 v[2:17], v[234:237], v[150:153], v[2:17]
	v_mfma_f32_32x32x16_bf16 v[34:49], v[238:241], v[138:141], v[34:49]
	v_mfma_f32_32x32x16_bf16 v[2:17], v[238:241], v[154:157], v[2:17]
	v_mfma_f32_32x32x16_bf16 v[34:49], v[242:245], v[142:145], v[34:49]
	v_mfma_f32_32x32x16_bf16 v[2:17], v[242:245], v[158:161], v[2:17]
	s_setprio 0
	s_barrier
	ds_read_b128 v[192:195], v250 offset:32768
	ds_read_b128 v[196:199], v251 offset:32768
	ds_read_b128 v[208:211], v252 offset:32768
	ds_read_b128 v[218:221], v233 offset:32768
	ds_read_b128 v[130:133], v246 offset:32768
	ds_read_b128 v[134:137], v247 offset:32768
	ds_read_b128 v[138:141], v248 offset:32768
	ds_read_b128 v[142:145], v249 offset:32768
	ds_read_b128 v[146:149], v246 offset:36864
	ds_read_b128 v[150:153], v247 offset:36864
	ds_read_b128 v[154:157], v248 offset:36864
	ds_read_b128 v[158:161], v249 offset:36864
	s_add_u32 m0, s4, 0x2000
	s_nop 0
	global_load_lds_dwordx4 v178, s[2:3]
	s_add_u32 m0, s4, 0x2400
	s_nop 0
	global_load_lds_dwordx4 v179, s[2:3]
	s_waitcnt lgkmcnt(8)
	s_barrier
	s_waitcnt lgkmcnt(0)
	s_setprio 1
	v_mfma_f32_32x32x16_bf16 v[114:129], v[192:195], v[130:133], v[114:129]
	v_mfma_f32_32x32x16_bf16 v[82:97], v[192:195], v[146:149], v[82:97]
	v_mfma_f32_32x32x16_bf16 v[114:129], v[196:199], v[134:137], v[114:129]
	v_mfma_f32_32x32x16_bf16 v[82:97], v[196:199], v[150:153], v[82:97]
	v_mfma_f32_32x32x16_bf16 v[114:129], v[208:211], v[138:141], v[114:129]
	v_mfma_f32_32x32x16_bf16 v[82:97], v[208:211], v[154:157], v[82:97]
	v_mfma_f32_32x32x16_bf16 v[114:129], v[218:221], v[142:145], v[114:129]
	v_mfma_f32_32x32x16_bf16 v[82:97], v[218:221], v[158:161], v[82:97]
	s_setprio 0
	s_barrier
	ds_read_b128 v[222:225], v250 offset:36864
	ds_read_b128 v[234:237], v251 offset:36864
	ds_read_b128 v[238:241], v252 offset:36864
	ds_read_b128 v[242:245], v233 offset:36864
	s_add_u32 s6, s6, 0x80
	s_addc_u32 s7, s7, 0
	s_add_u32 m0, s16, 0x8000
	s_nop 0
	global_load_lds_dwordx4 v228, s[6:7]
	s_add_u32 m0, s16, 0x8400
	s_nop 0
	global_load_lds_dwordx4 v214, s[6:7]
	s_barrier
	s_waitcnt lgkmcnt(0)
	s_setprio 1
	v_mfma_f32_32x32x16_bf16 v[98:113], v[222:225], v[130:133], v[98:113]
	v_mfma_f32_32x32x16_bf16 v[66:81], v[222:225], v[146:149], v[66:81]
	v_mfma_f32_32x32x16_bf16 v[98:113], v[234:237], v[134:137], v[98:113]
	v_mfma_f32_32x32x16_bf16 v[66:81], v[234:237], v[150:153], v[66:81]
	v_mfma_f32_32x32x16_bf16 v[98:113], v[238:241], v[138:141], v[98:113]
	v_mfma_f32_32x32x16_bf16 v[66:81], v[238:241], v[154:157], v[66:81]
	v_mfma_f32_32x32x16_bf16 v[98:113], v[242:245], v[142:145], v[98:113]
	v_mfma_f32_32x32x16_bf16 v[66:81], v[242:245], v[158:161], v[66:81]
	s_setprio 0
	s_barrier
	ds_read_b128 v[130:133], v246 offset:40960
	ds_read_b128 v[134:137], v247 offset:40960
	ds_read_b128 v[138:141], v248 offset:40960
	ds_read_b128 v[142:145], v249 offset:40960
	ds_read_b128 v[146:149], v246 offset:45056
	ds_read_b128 v[150:153], v247 offset:45056
	ds_read_b128 v[154:157], v248 offset:45056
	ds_read_b128 v[158:161], v249 offset:45056
	s_add_u32 s2, s2, 0x80
	s_addc_u32 s3, s3, 0
	s_add_u32 m0, s4, 0x8000
	s_nop 0
	global_load_lds_dwordx4 v226, s[2:3]
	s_add_u32 m0, s4, 0x8400
	s_nop 0
	global_load_lds_dwordx4 v227, s[2:3]
	s_barrier
	s_waitcnt lgkmcnt(0)
	s_setprio 1
	v_mfma_f32_32x32x16_bf16 v[50:65], v[192:195], v[130:133], v[50:65]
	v_mfma_f32_32x32x16_bf16 v[18:33], v[192:195], v[146:149], v[18:33]
	v_mfma_f32_32x32x16_bf16 v[50:65], v[196:199], v[134:137], v[50:65]
	v_mfma_f32_32x32x16_bf16 v[18:33], v[196:199], v[150:153], v[18:33]
	v_mfma_f32_32x32x16_bf16 v[50:65], v[208:211], v[138:141], v[50:65]
	v_mfma_f32_32x32x16_bf16 v[18:33], v[208:211], v[154:157], v[18:33]
	v_mfma_f32_32x32x16_bf16 v[50:65], v[218:221], v[142:145], v[50:65]
	v_mfma_f32_32x32x16_bf16 v[18:33], v[218:221], v[158:161], v[18:33]
	s_setprio 0
	s_barrier
	s_add_u32 m0, s16, 0x9000
	s_nop 0
	global_load_lds_dwordx4 v203, s[6:7]
	s_add_u32 m0, s16, 0x9400
	s_nop 0
	global_load_lds_dwordx4 v204, s[6:7]
	s_waitcnt vmcnt(6)
	s_barrier
	s_setprio 1
	v_mfma_f32_32x32x16_bf16 v[34:49], v[222:225], v[130:133], v[34:49]
	v_mfma_f32_32x32x16_bf16 v[2:17], v[222:225], v[146:149], v[2:17]
	v_mfma_f32_32x32x16_bf16 v[34:49], v[234:237], v[134:137], v[34:49]
	v_mfma_f32_32x32x16_bf16 v[2:17], v[234:237], v[150:153], v[2:17]
	v_mfma_f32_32x32x16_bf16 v[34:49], v[238:241], v[138:141], v[34:49]
	v_mfma_f32_32x32x16_bf16 v[2:17], v[238:241], v[154:157], v[2:17]
	v_mfma_f32_32x32x16_bf16 v[34:49], v[242:245], v[142:145], v[34:49]
	v_mfma_f32_32x32x16_bf16 v[2:17], v[242:245], v[158:161], v[2:17]
	s_setprio 0
	s_barrier
	s_mov_b32 s17, 2

.LBB0_72:
	s_ashr_i32 s1, s0, 31
	s_lshr_b32 s1, s1, 27
	s_add_i32 s1, s0, s1
	s_ashr_i32 s14, s1, 5
	s_andn2_b32 s1, s1, 31
	s_sub_i32 s1, s0, s1
	s_ashr_i32 s2, s1, 31
	s_lshr_b32 s2, s2, 29
	s_add_i32 s2, s1, s2
	s_ashr_i32 s2, s2, 3
	s_lshl_b32 s3, s14, 11
	s_lshl_b32 s1, s1, 8
	s_add_i32 s1, s1, s3
	s_lshl_b32 s15, s2, 11
	s_sub_i32 s1, s1, s15
	v_add_u32_e32 v2, s1, v165
	v_ashrrev_i32_e32 v3, 31, v2
	v_lshlrev_b64 v[2:3], 11, v[2:3]
	s_lshl_b32 s10, s2, 8
	v_lshl_add_u64 v[52:53], v[168:169], 0, v[2:3]
	s_mov_b32 s2, 0x20000
	v_add_u32_e32 v4, s10, v165
	v_add_co_u32_e32 v54, vcc, s2, v52
	v_ashrrev_i32_e32 v5, 31, v4
	s_nop 0
	v_addc_co_u32_e32 v55, vcc, 0, v53, vcc
	s_mov_b32 s3, 0x40000
	v_lshlrev_b64 v[48:49], 11, v[4:5]
	v_add_co_u32_e32 v56, vcc, s3, v52
	v_lshl_add_u64 v[50:51], v[166:167], 0, v[48:49]
	s_nop 0
	v_addc_co_u32_e32 v57, vcc, 0, v53, vcc
	v_add_co_u32_e32 v58, vcc, s2, v50
	s_mov_b32 s2, 0x60000
	s_nop 0
	v_addc_co_u32_e32 v59, vcc, 0, v51, vcc
	v_add_co_u32_e32 v60, vcc, s3, v50
	v_addc_co_u32_e32 v61, vcc, 0, v51, vcc
	v_add_co_u32_e32 v62, vcc, s2, v50
	v_addc_co_u32_e32 v63, vcc, 0, v51, vcc
	v_add_co_u32_e32 v64, vcc, s2, v52
	v_addc_co_u32_e32 v65, vcc, 0, v53, vcc
	s_mulk_i32 s14, 0x1800
	v_subrev_u32_e32 v15, s15, v191
	v_subrev_u32_e32 v66, s14, v15
	v_ashrrev_i32_e32 v67, 31, v66
	v_lshl_add_u64 v[178:179], v[174:175], 0, v[48:49]
	v_lshlrev_b64 v[48:49], 11, v[66:67]
	s_mov_b64 s[2:3], 0
	s_mov_b32 s13, 1
	v_lshl_add_u64 v[180:181], v[176:177], 0, v[48:49]
	s_mov_b32 s4, 0x308d000
	s_mov_b32 s5, 0x30ad000
	s_mov_b32 s6, 0x30cd000
	s_waitcnt lgkmcnt(0)
	v_lshrrev_b32_e32 v130, 6, v200
	v_and_b32_e32 v131, 63, v200
	v_readfirstlane_b32 s14, v130
	s_lshr_b32 s6, s14, 2
	s_lshl_b32 s6, s6, 7
	s_and_b32 s15, s14, 3
	s_lshl_b32 s15, s15, 4
	s_add_u32 s6, s6, s15
	s_add_u32 s15, s6, s1
	s_mul_i32 s15, s15, 2048
	s_add_u32 s2, s36, 0x308d800
	s_addc_u32 s3, s37, 0
	s_add_u32 s2, s2, s15
	s_addc_u32 s3, s3, 0
	s_lshl_b32 s6, s6, 7
	s_lshr_b32 s13, s14, 1
	s_lshl_b32 s13, s13, 6
	s_and_b32 s15, s14, 1
	s_lshl_b32 s15, s15, 4
	s_add_u32 s13, s13, s15
	v_readlane_b32 s5, v255, 30
	s_nop 3
	s_mul_i32 s5, s5, 0x200000
	s_add_u32 s4, s36, s5
	s_addc_u32 s5, s37, 0
	s_add_u32 s4, s4, 0x86d800
	s_addc_u32 s5, s5, 0
	s_add_u32 s15, s13, s10
	s_mul_i32 s15, s15, 2048
	s_add_u32 s4, s4, s15
	s_addc_u32 s5, s5, 0
	s_lshl_b32 s13, s13, 7
	s_add_u32 s13, s13, 0x10000
	v_lshrrev_b32_e32 v132, 3, v131
	v_and_b32_e32 v133, 7, v131
	v_lshrrev_b32_e32 v134, 4, v131
	v_xor_b32_e32 v133, v133, v134
	v_lshlrev_b32_e32 v133, 4, v133
	v_mul_u32_u24_e32 v134, 2048, v132
	v_or_b32_e32 v226, v134, v133
	v_add_u32_e32 v227, 16384, v226
	v_xor_b32_e32 v227, 64, v227
	v_add_u32_e32 v178, 0x20000, v226
	v_add_u32_e32 v179, 0x20000, v227
	v_mul_u32_u24_e32 v134, 2048, v132
	v_or_b32_e32 v228, v134, v133
	v_add_u32_e32 v214, 16384, v228
	v_xor_b32_e32 v214, 64, v214
	v_add_u32_e32 v203, 0x10000, v228
	v_add_u32_e32 v204, 0x10000, v214
	v_and_b32_e32 v132, 31, v131
	v_lshrrev_b32_e32 v133, 5, v131
	v_bfe_u32 v134, v132, 1, 3
	v_and_b32_e32 v135, 1, v134
	v_xor_b32_e32 v133, v133, v135
	v_lshlrev_b32_e32 v133, 4, v133
	v_lshl_add_u32 v133, v132, 7, v133
	v_and_b32_e32 v134, 6, v134
	s_lshr_b32 s15, s14, 2
	s_lshl_b32 s15, s15, 14
	v_xor_b32_e32 v135, 0, v134
	v_lshl_add_u32 v135, v135, 4, v133
	v_add_u32_e32 v246, s15, v135
	v_xor_b32_e32 v135, 2, v134
	v_lshl_add_u32 v135, v135, 4, v133
	v_add_u32_e32 v247, s15, v135
	v_xor_b32_e32 v135, 4, v134
	v_lshl_add_u32 v135, v135, 4, v133
	v_add_u32_e32 v248, s15, v135
	v_xor_b32_e32 v135, 6, v134
	v_lshl_add_u32 v135, v135, 4, v133
	v_add_u32_e32 v249, s15, v135
	s_and_b32 s15, s14, 3
	s_lshl_b32 s15, s15, 13
	s_add_u32 s15, s15, 0x10000
	v_xor_b32_e32 v135, 0, v134
	v_lshl_add_u32 v135, v135, 4, v133
	v_add_u32_e32 v250, s15, v135
	v_xor_b32_e32 v135, 2, v134
	v_lshl_add_u32 v135, v135, 4, v133
	v_add_u32_e32 v251, s15, v135
	v_xor_b32_e32 v135, 4, v134
	v_lshl_add_u32 v135, v135, 4, v133
	v_add_u32_e32 v252, s15, v135
	v_xor_b32_e32 v135, 6, v134
	v_lshl_add_u32 v135, v135, 4, v133
	v_add_u32_e32 v233, s15, v135
	s_add_u32 m0, s13, 0x0
	s_nop 0
	global_load_lds_dwordx4 v228, s[4:5]
	s_add_u32 m0, s13, 0x400
	s_nop 0
	global_load_lds_dwordx4 v214, s[4:5]
	s_add_u32 m0, s6, 0x0
	s_nop 0
	global_load_lds_dwordx4 v226, s[2:3]
	s_add_u32 m0, s6, 0x400
	s_nop 0
	global_load_lds_dwordx4 v227, s[2:3]
	s_add_u32 m0, s13, 0x1000
	s_nop 0
	global_load_lds_dwordx4 v203, s[4:5]
	s_add_u32 m0, s13, 0x1400
	s_nop 0
	global_load_lds_dwordx4 v204, s[4:5]
	s_add_u32 m0, s6, 0x2000
	s_nop 0
	global_load_lds_dwordx4 v178, s[2:3]
	s_add_u32 m0, s6, 0x2400
	s_nop 0
	global_load_lds_dwordx4 v179, s[2:3]
	v_readfirstlane_b32 s15, v200
	s_lshr_b32 s15, s15, 8
	s_cmp_lg_u32 s15, 0
	s_cbranch_scc0 .Lgou_nolag
	s_barrier
.Lgou_nolag:
	s_waitcnt vmcnt(4)
	s_barrier
	s_add_u32 s4, s4, 0x80
	s_addc_u32 s5, s5, 0
	s_add_u32 m0, s13, 0x8000
	s_nop 0
	global_load_lds_dwordx4 v228, s[4:5]
	s_add_u32 m0, s13, 0x8400
	s_nop 0
	global_load_lds_dwordx4 v214, s[4:5]
	s_add_u32 s2, s2, 0x80
	s_addc_u32 s3, s3, 0
	s_add_u32 m0, s6, 0x8000
	s_nop 0
	global_load_lds_dwordx4 v226, s[2:3]
	s_add_u32 m0, s6, 0x8400
	s_nop 0
	global_load_lds_dwordx4 v227, s[2:3]
	s_add_u32 m0, s13, 0x9000
	s_nop 0
	global_load_lds_dwordx4 v203, s[4:5]
	s_add_u32 m0, s13, 0x9400
	s_nop 0
	global_load_lds_dwordx4 v204, s[4:5]
	s_waitcnt vmcnt(6)
	s_barrier
	ds_read_b128 v[192:195], v250
	ds_read_b128 v[196:199], v251
	ds_read_b128 v[208:211], v252
	ds_read_b128 v[218:221], v233
	ds_read_b128 v[130:133], v246 offset:0
	ds_read_b128 v[134:137], v247 offset:0
	ds_read_b128 v[138:141], v248 offset:0
	ds_read_b128 v[142:145], v249 offset:0
	ds_read_b128 v[146:149], v246 offset:4096
	ds_read_b128 v[150:153], v247 offset:4096
	ds_read_b128 v[154:157], v248 offset:4096
	ds_read_b128 v[158:161], v249 offset:4096
	s_add_u32 m0, s6, 0xa000
	s_nop 0
	global_load_lds_dwordx4 v178, s[2:3]
	s_add_u32 m0, s6, 0xa400
	s_nop 0
	global_load_lds_dwordx4 v179, s[2:3]
	s_waitcnt lgkmcnt(8)
	s_barrier
	s_waitcnt lgkmcnt(0)
	s_setprio 1
	v_mfma_f32_32x32x16_bf16 v[114:129], v[192:195], v[130:133], 0
	v_mfma_f32_32x32x16_bf16 v[82:97], v[192:195], v[146:149], 0
	v_mfma_f32_32x32x16_bf16 v[114:129], v[196:199], v[134:137], v[114:129]
	v_mfma_f32_32x32x16_bf16 v[82:97], v[196:199], v[150:153], v[82:97]
	v_mfma_f32_32x32x16_bf16 v[114:129], v[208:211], v[138:141], v[114:129]
	v_mfma_f32_32x32x16_bf16 v[82:97], v[208:211], v[154:157], v[82:97]
	v_mfma_f32_32x32x16_bf16 v[114:129], v[218:221], v[142:145], v[114:129]
	v_mfma_f32_32x32x16_bf16 v[82:97], v[218:221], v[158:161], v[82:97]
	s_setprio 0
	s_barrier
	ds_read_b128 v[222:225], v250 offset:4096
	ds_read_b128 v[234:237], v251 offset:4096
	ds_read_b128 v[238:241], v252 offset:4096
	ds_read_b128 v[242:245], v233 offset:4096
	s_add_u32 s4, s4, 0x80
	s_addc_u32 s5, s5, 0
	s_add_u32 m0, s13, 0x0
	s_nop 0
	global_load_lds_dwordx4 v228, s[4:5]
	s_add_u32 m0, s13, 0x400
	s_nop 0
	global_load_lds_dwordx4 v214, s[4:5]
	s_barrier
	s_waitcnt lgkmcnt(0)
	s_setprio 1
	v_mfma_f32_32x32x16_bf16 v[98:113], v[222:225], v[130:133], 0
	v_mfma_f32_32x32x16_bf16 v[66:81], v[222:225], v[146:149], 0
	v_mfma_f32_32x32x16_bf16 v[98:113], v[234:237], v[134:137], v[98:113]
	v_mfma_f32_32x32x16_bf16 v[66:81], v[234:237], v[150:153], v[66:81]
	v_mfma_f32_32x32x16_bf16 v[98:113], v[238:241], v[138:141], v[98:113]
	v_mfma_f32_32x32x16_bf16 v[66:81], v[238:241], v[154:157], v[66:81]
	v_mfma_f32_32x32x16_bf16 v[98:113], v[242:245], v[142:145], v[98:113]
	v_mfma_f32_32x32x16_bf16 v[66:81], v[242:245], v[158:161], v[66:81]
	s_setprio 0
	s_barrier
	ds_read_b128 v[130:133], v246 offset:8192
	ds_read_b128 v[134:137], v247 offset:8192
	ds_read_b128 v[138:141], v248 offset:8192
	ds_read_b128 v[142:145], v249 offset:8192
	ds_read_b128 v[146:149], v246 offset:12288
	ds_read_b128 v[150:153], v247 offset:12288
	ds_read_b128 v[154:157], v248 offset:12288
	ds_read_b128 v[158:161], v249 offset:12288
	s_add_u32 s2, s2, 0x80
	s_addc_u32 s3, s3, 0
	s_add_u32 m0, s6, 0x0
	s_nop 0
	global_load_lds_dwordx4 v226, s[2:3]
	s_add_u32 m0, s6, 0x400
	s_nop 0
	global_load_lds_dwordx4 v227, s[2:3]
	s_barrier
	s_waitcnt lgkmcnt(0)
	s_setprio 1
	v_mfma_f32_32x32x16_bf16 v[50:65], v[192:195], v[130:133], 0
	v_mfma_f32_32x32x16_bf16 v[18:33], v[192:195], v[146:149], 0
	v_mfma_f32_32x32x16_bf16 v[50:65], v[196:199], v[134:137], v[50:65]
	v_mfma_f32_32x32x16_bf16 v[18:33], v[196:199], v[150:153], v[18:33]
	v_mfma_f32_32x32x16_bf16 v[50:65], v[208:211], v[138:141], v[50:65]
	v_mfma_f32_32x32x16_bf16 v[18:33], v[208:211], v[154:157], v[18:33]
	v_mfma_f32_32x32x16_bf16 v[50:65], v[218:221], v[142:145], v[50:65]
	v_mfma_f32_32x32x16_bf16 v[18:33], v[218:221], v[158:161], v[18:33]
	s_setprio 0
	s_barrier
	s_add_u32 m0, s13, 0x1000
	s_nop 0
	global_load_lds_dwordx4 v203, s[4:5]
	s_add_u32 m0, s13, 0x1400
	s_nop 0
	global_load_lds_dwordx4 v204, s[4:5]
	s_waitcnt vmcnt(6)
	s_barrier
	s_setprio 1
	v_mfma_f32_32x32x16_bf16 v[34:49], v[222:225], v[130:133], 0
	v_mfma_f32_32x32x16_bf16 v[2:17], v[222:225], v[146:149], 0
	v_mfma_f32_32x32x16_bf16 v[34:49], v[234:237], v[134:137], v[34:49]
	v_mfma_f32_32x32x16_bf16 v[2:17], v[234:237], v[150:153], v[2:17]
	v_mfma_f32_32x32x16_bf16 v[34:49], v[238:241], v[138:141], v[34:49]
	v_mfma_f32_32x32x16_bf16 v[2:17], v[238:241], v[154:157], v[2:17]
	v_mfma_f32_32x32x16_bf16 v[34:49], v[242:245], v[142:145], v[34:49]
	v_mfma_f32_32x32x16_bf16 v[2:17], v[242:245], v[158:161], v[2:17]
	s_setprio 0
	s_barrier
	ds_read_b128 v[192:195], v250 offset:32768
	ds_read_b128 v[196:199], v251 offset:32768
	ds_read_b128 v[208:211], v252 offset:32768
	ds_read_b128 v[218:221], v233 offset:32768
	ds_read_b128 v[130:133], v246 offset:32768
	ds_read_b128 v[134:137], v247 offset:32768
	ds_read_b128 v[138:141], v248 offset:32768
	ds_read_b128 v[142:145], v249 offset:32768
	ds_read_b128 v[146:149], v246 offset:36864
	ds_read_b128 v[150:153], v247 offset:36864
	ds_read_b128 v[154:157], v248 offset:36864
	ds_read_b128 v[158:161], v249 offset:36864
	s_add_u32 m0, s6, 0x2000
	s_nop 0
	global_load_lds_dwordx4 v178, s[2:3]
	s_add_u32 m0, s6, 0x2400
	s_nop 0
	global_load_lds_dwordx4 v179, s[2:3]
	s_waitcnt lgkmcnt(8)
	s_barrier
	s_waitcnt lgkmcnt(0)
	s_setprio 1
	v_mfma_f32_32x32x16_bf16 v[114:129], v[192:195], v[130:133], v[114:129]
	v_mfma_f32_32x32x16_bf16 v[82:97], v[192:195], v[146:149], v[82:97]
	v_mfma_f32_32x32x16_bf16 v[114:129], v[196:199], v[134:137], v[114:129]
	v_mfma_f32_32x32x16_bf16 v[82:97], v[196:199], v[150:153], v[82:97]
	v_mfma_f32_32x32x16_bf16 v[114:129], v[208:211], v[138:141], v[114:129]
	v_mfma_f32_32x32x16_bf16 v[82:97], v[208:211], v[154:157], v[82:97]
	v_mfma_f32_32x32x16_bf16 v[114:129], v[218:221], v[142:145], v[114:129]
	v_mfma_f32_32x32x16_bf16 v[82:97], v[218:221], v[158:161], v[82:97]
	s_setprio 0
	s_barrier
	ds_read_b128 v[222:225], v250 offset:36864
	ds_read_b128 v[234:237], v251 offset:36864
	ds_read_b128 v[238:241], v252 offset:36864
	ds_read_b128 v[242:245], v233 offset:36864
	s_add_u32 s4, s4, 0x80
	s_addc_u32 s5, s5, 0
	s_add_u32 m0, s13, 0x8000
	s_nop 0
	global_load_lds_dwordx4 v228, s[4:5]
	s_add_u32 m0, s13, 0x8400
	s_nop 0
	global_load_lds_dwordx4 v214, s[4:5]
	s_barrier
	s_waitcnt lgkmcnt(0)
	s_setprio 1
	v_mfma_f32_32x32x16_bf16 v[98:113], v[222:225], v[130:133], v[98:113]
	v_mfma_f32_32x32x16_bf16 v[66:81], v[222:225], v[146:149], v[66:81]
	v_mfma_f32_32x32x16_bf16 v[98:113], v[234:237], v[134:137], v[98:113]
	v_mfma_f32_32x32x16_bf16 v[66:81], v[234:237], v[150:153], v[66:81]
	v_mfma_f32_32x32x16_bf16 v[98:113], v[238:241], v[138:141], v[98:113]
	v_mfma_f32_32x32x16_bf16 v[66:81], v[238:241], v[154:157], v[66:81]
	v_mfma_f32_32x32x16_bf16 v[98:113], v[242:245], v[142:145], v[98:113]
	v_mfma_f32_32x32x16_bf16 v[66:81], v[242:245], v[158:161], v[66:81]
	s_setprio 0
	s_barrier
	ds_read_b128 v[130:133], v246 offset:40960
	ds_read_b128 v[134:137], v247 offset:40960
	ds_read_b128 v[138:141], v248 offset:40960
	ds_read_b128 v[142:145], v249 offset:40960
	ds_read_b128 v[146:149], v246 offset:45056
	ds_read_b128 v[150:153], v247 offset:45056
	ds_read_b128 v[154:157], v248 offset:45056
	ds_read_b128 v[158:161], v249 offset:45056
	s_add_u32 s2, s2, 0x80
	s_addc_u32 s3, s3, 0
	s_add_u32 m0, s6, 0x8000
	s_nop 0
	global_load_lds_dwordx4 v226, s[2:3]
	s_add_u32 m0, s6, 0x8400
	s_nop 0
	global_load_lds_dwordx4 v227, s[2:3]
	s_barrier
	s_waitcnt lgkmcnt(0)
	s_setprio 1
	v_mfma_f32_32x32x16_bf16 v[50:65], v[192:195], v[130:133], v[50:65]
	v_mfma_f32_32x32x16_bf16 v[18:33], v[192:195], v[146:149], v[18:33]
	v_mfma_f32_32x32x16_bf16 v[50:65], v[196:199], v[134:137], v[50:65]
	v_mfma_f32_32x32x16_bf16 v[18:33], v[196:199], v[150:153], v[18:33]
	v_mfma_f32_32x32x16_bf16 v[50:65], v[208:211], v[138:141], v[50:65]
	v_mfma_f32_32x32x16_bf16 v[18:33], v[208:211], v[154:157], v[18:33]
	v_mfma_f32_32x32x16_bf16 v[50:65], v[218:221], v[142:145], v[50:65]
	v_mfma_f32_32x32x16_bf16 v[18:33], v[218:221], v[158:161], v[18:33]
	s_setprio 0
	s_barrier
	s_add_u32 m0, s13, 0x9000
	s_nop 0
	global_load_lds_dwordx4 v203, s[4:5]
	s_add_u32 m0, s13, 0x9400
	s_nop 0
	global_load_lds_dwordx4 v204, s[4:5]
	s_waitcnt vmcnt(6)
	s_barrier
	s_setprio 1
	v_mfma_f32_32x32x16_bf16 v[34:49], v[222:225], v[130:133], v[34:49]
	v_mfma_f32_32x32x16_bf16 v[2:17], v[222:225], v[146:149], v[2:17]
	v_mfma_f32_32x32x16_bf16 v[34:49], v[234:237], v[134:137], v[34:49]
	v_mfma_f32_32x32x16_bf16 v[2:17], v[234:237], v[150:153], v[2:17]
	v_mfma_f32_32x32x16_bf16 v[34:49], v[238:241], v[138:141], v[34:49]
	v_mfma_f32_32x32x16_bf16 v[2:17], v[238:241], v[154:157], v[2:17]
	v_mfma_f32_32x32x16_bf16 v[34:49], v[242:245], v[142:145], v[34:49]
	v_mfma_f32_32x32x16_bf16 v[2:17], v[242:245], v[158:161], v[2:17]
	s_setprio 0
	s_barrier
	s_mov_b32 s14, 2

.LBB0_215:
	s_mul_hi_i32 s0, s10, 0x92492493
	s_add_i32 s0, s0, s10
	s_lshr_b32 s1, s0, 31
	s_ashr_i32 s0, s0, 5
	s_add_i32 s13, s0, s1
	s_lshl_b32 s0, s13, 3
	s_sub_i32 s1, 0x42, s0
	s_min_u32 s1, s1, 8
	v_cvt_f32_ubyte0_e32 v0, s1
	v_rcp_iflag_f32_e32 v0, v0
	s_sub_i32 s14, 0, s1
	s_mul_i32 s2, s13, 0xffffffc8
	s_add_i32 s2, s2, s10
	v_mul_f32_e32 v0, 0x4f7ffffe, v0
	v_cvt_u32_f32_e32 v0, v0
	s_abs_i32 s12, s2
	s_ashr_i32 s3, s2, 31
	s_mul_i32 s13, s13, 48
	v_readfirstlane_b32 s15, v0
	s_mul_i32 s14, s14, s15
	s_mul_hi_u32 s14, s15, s14
	s_add_i32 s15, s15, s14
	s_mul_hi_u32 s14, s12, s15
	s_mul_i32 s15, s14, s1
	s_sub_i32 s12, s12, s15
	s_add_i32 s15, s14, 1
	s_sub_i32 s16, s12, s1
	s_cmp_ge_u32 s12, s1
	s_cselect_b32 s14, s15, s14
	s_cselect_b32 s12, s16, s12
	s_add_i32 s15, s14, 1
	s_cmp_ge_u32 s12, s1
	s_cselect_b32 s12, s15, s14
	s_xor_b32 s12, s12, s3
	s_sub_i32 s3, s12, s3
	s_mul_i32 s14, s3, s1
	s_add_i32 s2, s2, s0
	s_sub_i32 s0, s2, s14
	s_lshl_b32 s1, s0, 8
	v_add_u32_e32 v2, s1, v164
	v_ashrrev_i32_e32 v3, 31, v2
	v_lshlrev_b64 v[2:3], 11, v[2:3]
	s_lshl_b32 s0, s3, 8
	v_lshl_add_u64 v[50:51], v[168:169], 0, v[2:3]
	v_add_u32_e32 v4, s0, v164
	v_add_co_u32_e32 v52, vcc, s7, v50
	v_ashrrev_i32_e32 v5, 31, v4
	s_nop 0
	v_addc_co_u32_e32 v53, vcc, 0, v51, vcc
	v_lshlrev_b64 v[46:47], 11, v[4:5]
	v_add_co_u32_e32 v54, vcc, s8, v50
	v_lshl_add_u64 v[48:49], v[166:167], 0, v[46:47]
	s_nop 0
	v_addc_co_u32_e32 v55, vcc, 0, v51, vcc
	v_add_co_u32_e32 v56, vcc, s7, v48
	v_addc_co_u32_e32 v57, vcc, 0, v49, vcc
	v_add_co_u32_e32 v58, vcc, s8, v48
	v_addc_co_u32_e32 v59, vcc, 0, v49, vcc
	v_add_co_u32_e32 v60, vcc, s9, v48
	v_addc_co_u32_e32 v61, vcc, 0, v49, vcc
	v_add_co_u32_e32 v62, vcc, s9, v50
	v_addc_co_u32_e32 v63, vcc, 0, v51, vcc
	s_sub_i32 s14, s10, s14
	s_sub_i32 s13, s14, s13
	s_lshl_b32 s14, s13, 8
	s_ashr_i32 s15, s14, 31
	v_lshl_add_u64 v[196:197], v[192:193], 0, v[46:47]
	v_lshl_add_u64 v[46:47], v[164:165], 0, s[14:15]
	v_lshlrev_b64 v[46:47], 11, v[46:47]
	s_mov_b32 s12, 1
	s_mov_b64 s[2:3], 0
	v_lshl_add_u64 v[198:199], v[194:195], 0, v[46:47]
	s_waitcnt lgkmcnt(0)
	v_lshrrev_b32_e32 v130, 6, v200
	v_and_b32_e32 v131, 63, v200
	v_readfirstlane_b32 s41, v130
	s_lshr_b32 s16, s41, 2
	s_lshl_b32 s16, s16, 7
	s_and_b32 s42, s41, 3
	s_lshl_b32 s42, s42, 4
	s_add_u32 s16, s16, s42
	s_add_u32 s42, s16, s1
	s_mul_i32 s42, s42, 2048
	s_add_u32 s2, s36, 0x308d800
	s_addc_u32 s3, s37, 0
	s_add_u32 s2, s2, s42
	s_addc_u32 s3, s3, 0
	s_lshl_b32 s16, s16, 7
	s_lshr_b32 s40, s41, 1
	s_lshl_b32 s40, s40, 6
	s_and_b32 s42, s41, 1
	s_lshl_b32 s42, s42, 4
	s_add_u32 s40, s40, s42
	v_readlane_b32 s15, v255, 30
	s_nop 3
	s_mul_i32 s15, s15, 0x400000
	s_add_u32 s14, s36, s15
	s_addc_u32 s15, s37, 0
	s_add_u32 s14, s14, 0x6d800
	s_addc_u32 s15, s15, 0
	s_add_u32 s42, s40, s0
	s_mul_i32 s42, s42, 2048
	s_add_u32 s14, s14, s42
	s_addc_u32 s15, s15, 0
	s_lshl_b32 s40, s40, 7
	s_add_u32 s40, s40, 0x10000
	s_add_u32 s12, s2, 0x20000
	s_addc_u32 s13, s3, 0
	s_add_u32 s22, s14, 0x10000
	s_addc_u32 s23, s15, 0
	v_lshrrev_b32_e32 v132, 3, v131
	v_and_b32_e32 v133, 7, v131
	v_lshrrev_b32_e32 v134, 4, v131
	v_xor_b32_e32 v133, v133, v134
	v_lshlrev_b32_e32 v133, 4, v133
	v_mul_u32_u24_e32 v134, 2048, v132
	v_or_b32_e32 v227, v134, v133
	v_add_u32_e32 v228, 16384, v227
	v_xor_b32_e32 v228, 64, v228
	v_and_b32_e32 v132, 31, v131
	v_lshrrev_b32_e32 v133, 5, v131
	v_bfe_u32 v134, v132, 1, 3
	v_and_b32_e32 v135, 1, v134
	v_xor_b32_e32 v133, v133, v135
	v_lshlrev_b32_e32 v133, 4, v133
	v_lshl_add_u32 v133, v132, 7, v133
	v_and_b32_e32 v134, 6, v134
	s_lshr_b32 s42, s41, 2
	s_lshl_b32 s42, s42, 14
	v_xor_b32_e32 v135, 0, v134
	v_lshl_add_u32 v135, v135, 4, v133
	v_add_u32_e32 v192, s42, v135
	v_xor_b32_e32 v135, 2, v134
	v_lshl_add_u32 v135, v135, 4, v133
	v_add_u32_e32 v193, s42, v135
	v_xor_b32_e32 v135, 4, v134
	v_lshl_add_u32 v135, v135, 4, v133
	v_add_u32_e32 v194, s42, v135
	v_xor_b32_e32 v135, 6, v134
	v_lshl_add_u32 v135, v135, 4, v133
	v_add_u32_e32 v195, s42, v135
	s_and_b32 s42, s41, 3
	s_lshl_b32 s42, s42, 13
	s_add_u32 s42, s42, 0x10000
	v_xor_b32_e32 v135, 0, v134
	v_lshl_add_u32 v135, v135, 4, v133
	v_add_u32_e32 v203, s42, v135
	v_xor_b32_e32 v135, 2, v134
	v_lshl_add_u32 v135, v135, 4, v133
	v_add_u32_e32 v204, s42, v135
	v_xor_b32_e32 v135, 4, v134
	v_lshl_add_u32 v135, v135, 4, v133
	v_add_u32_e32 v214, s42, v135
	v_xor_b32_e32 v135, 6, v134
	v_lshl_add_u32 v135, v135, 4, v133
	v_add_u32_e32 v226, s42, v135
	s_add_u32 m0, s40, 0x0
	s_nop 0
	global_load_lds_dwordx4 v227, s[14:15]
	s_add_u32 m0, s40, 0x400
	s_nop 0
	global_load_lds_dwordx4 v228, s[14:15]
	s_add_u32 s14, s14, 0x80
	s_addc_u32 s15, s15, 0
	s_add_u32 m0, s16, 0x0
	s_nop 0
	global_load_lds_dwordx4 v227, s[2:3]
	s_add_u32 m0, s16, 0x400
	s_nop 0
	global_load_lds_dwordx4 v228, s[2:3]
	s_add_u32 s2, s2, 0x80
	s_addc_u32 s3, s3, 0
	s_add_u32 m0, s40, 0x1000
	s_nop 0
	global_load_lds_dwordx4 v227, s[22:23]
	s_add_u32 m0, s40, 0x1400
	s_nop 0
	global_load_lds_dwordx4 v228, s[22:23]
	s_add_u32 s22, s22, 0x80
	s_addc_u32 s23, s23, 0
	s_add_u32 m0, s16, 0x2000
	s_nop 0
	global_load_lds_dwordx4 v227, s[12:13]
	s_add_u32 m0, s16, 0x2400
	s_nop 0
	global_load_lds_dwordx4 v228, s[12:13]
	s_add_u32 s12, s12, 0x80
	s_addc_u32 s13, s13, 0
	v_readfirstlane_b32 s42, v200
	s_lshr_b32 s42, s42, 8
	s_cmp_lg_u32 s42, 0
	s_cbranch_scc0 .Lgin_nolag
	s_barrier
.Lgin_nolag:
	s_waitcnt vmcnt(4)
	s_barrier
	s_add_u32 m0, s40, 0x8000
	s_nop 0
	global_load_lds_dwordx4 v227, s[14:15]
	s_add_u32 m0, s40, 0x8400
	s_nop 0
	global_load_lds_dwordx4 v228, s[14:15]
	s_add_u32 s14, s14, 0x80
	s_addc_u32 s15, s15, 0
	s_add_u32 m0, s16, 0x8000
	s_nop 0
	global_load_lds_dwordx4 v227, s[2:3]
	s_add_u32 m0, s16, 0x8400
	s_nop 0
	global_load_lds_dwordx4 v228, s[2:3]
	s_add_u32 s2, s2, 0x80
	s_addc_u32 s3, s3, 0
	s_add_u32 m0, s40, 0x9000
	s_nop 0
	global_load_lds_dwordx4 v227, s[22:23]
	s_add_u32 m0, s40, 0x9400
	s_nop 0
	global_load_lds_dwordx4 v228, s[22:23]
	s_add_u32 s22, s22, 0x80
	s_addc_u32 s23, s23, 0
	s_waitcnt vmcnt(6)
	s_barrier
	ds_read_b128 v[196:199], v203
	ds_read_b128 v[208:211], v204
	ds_read_b128 v[218:221], v214
	ds_read_b128 v[222:225], v226
	ds_read_b128 v[130:133], v192 offset:0
	ds_read_b128 v[134:137], v193 offset:0
	ds_read_b128 v[138:141], v194 offset:0
	ds_read_b128 v[142:145], v195 offset:0
	ds_read_b128 v[146:149], v192 offset:4096
	ds_read_b128 v[150:153], v193 offset:4096
	ds_read_b128 v[154:157], v194 offset:4096
	ds_read_b128 v[158:161], v195 offset:4096
	s_add_u32 m0, s16, 0xa000
	s_nop 0
	global_load_lds_dwordx4 v227, s[12:13]
	s_add_u32 m0, s16, 0xa400
	s_nop 0
	global_load_lds_dwordx4 v228, s[12:13]
	s_add_u32 s12, s12, 0x80
	s_addc_u32 s13, s13, 0
	s_waitcnt lgkmcnt(8)
	s_barrier
	s_waitcnt lgkmcnt(0)
	s_setprio 1
	v_mfma_f32_32x32x16_bf16 v[114:129], v[196:199], v[130:133], 0
	v_mfma_f32_32x32x16_bf16 v[82:97], v[196:199], v[146:149], 0
	v_mfma_f32_32x32x16_bf16 v[114:129], v[208:211], v[134:137], v[114:129]
	v_mfma_f32_32x32x16_bf16 v[82:97], v[208:211], v[150:153], v[82:97]
	v_mfma_f32_32x32x16_bf16 v[114:129], v[218:221], v[138:141], v[114:129]
	v_mfma_f32_32x32x16_bf16 v[82:97], v[218:221], v[154:157], v[82:97]
	v_mfma_f32_32x32x16_bf16 v[114:129], v[222:225], v[142:145], v[114:129]
	v_mfma_f32_32x32x16_bf16 v[82:97], v[222:225], v[158:161], v[82:97]
	s_setprio 0
	s_barrier
	ds_read_b128 v[236:239], v203 offset:4096
	ds_read_b128 v[240:243], v204 offset:4096
	ds_read_b128 v[244:247], v214 offset:4096
	ds_read_b128 v[248:251], v226 offset:4096
	s_add_u32 m0, s40, 0x0
	s_nop 0
	global_load_lds_dwordx4 v227, s[14:15]
	s_add_u32 m0, s40, 0x400
	s_nop 0
	global_load_lds_dwordx4 v228, s[14:15]
	s_add_u32 s14, s14, 0x80
	s_addc_u32 s15, s15, 0
	s_barrier
	s_waitcnt lgkmcnt(0)
	s_setprio 1
	v_mfma_f32_32x32x16_bf16 v[98:113], v[236:239], v[130:133], 0
	v_mfma_f32_32x32x16_bf16 v[66:81], v[236:239], v[146:149], 0
	v_mfma_f32_32x32x16_bf16 v[98:113], v[240:243], v[134:137], v[98:113]
	v_mfma_f32_32x32x16_bf16 v[66:81], v[240:243], v[150:153], v[66:81]
	v_mfma_f32_32x32x16_bf16 v[98:113], v[244:247], v[138:141], v[98:113]
	v_mfma_f32_32x32x16_bf16 v[66:81], v[244:247], v[154:157], v[66:81]
	v_mfma_f32_32x32x16_bf16 v[98:113], v[248:251], v[142:145], v[98:113]
	v_mfma_f32_32x32x16_bf16 v[66:81], v[248:251], v[158:161], v[66:81]
	s_setprio 0
	s_barrier
	ds_read_b128 v[130:133], v192 offset:8192
	ds_read_b128 v[134:137], v193 offset:8192
	ds_read_b128 v[138:141], v194 offset:8192
	ds_read_b128 v[142:145], v195 offset:8192
	ds_read_b128 v[146:149], v192 offset:12288
	ds_read_b128 v[150:153], v193 offset:12288
	ds_read_b128 v[154:157], v194 offset:12288
	ds_read_b128 v[158:161], v195 offset:12288
	s_add_u32 m0, s16, 0x0
	s_nop 0
	global_load_lds_dwordx4 v227, s[2:3]
	s_add_u32 m0, s16, 0x400
	s_nop 0
	global_load_lds_dwordx4 v228, s[2:3]
	s_add_u32 s2, s2, 0x80
	s_addc_u32 s3, s3, 0
	s_barrier
	s_waitcnt lgkmcnt(0)
	s_setprio 1
	v_mfma_f32_32x32x16_bf16 v[50:65], v[196:199], v[130:133], 0
	v_mfma_f32_32x32x16_bf16 v[18:33], v[196:199], v[146:149], 0
	v_mfma_f32_32x32x16_bf16 v[50:65], v[208:211], v[134:137], v[50:65]
	v_mfma_f32_32x32x16_bf16 v[18:33], v[208:211], v[150:153], v[18:33]
	v_mfma_f32_32x32x16_bf16 v[50:65], v[218:221], v[138:141], v[50:65]
	v_mfma_f32_32x32x16_bf16 v[18:33], v[218:221], v[154:157], v[18:33]
	v_mfma_f32_32x32x16_bf16 v[50:65], v[222:225], v[142:145], v[50:65]
	v_mfma_f32_32x32x16_bf16 v[18:33], v[222:225], v[158:161], v[18:33]
	s_setprio 0
	s_barrier
	s_add_u32 m0, s40, 0x1000
	s_nop 0
	global_load_lds_dwordx4 v227, s[22:23]
	s_add_u32 m0, s40, 0x1400
	s_nop 0
	global_load_lds_dwordx4 v228, s[22:23]
	s_add_u32 s22, s22, 0x80
	s_addc_u32 s23, s23, 0
	s_waitcnt vmcnt(6)
	s_barrier
	s_setprio 1
	v_mfma_f32_32x32x16_bf16 v[34:49], v[236:239], v[130:133], 0
	v_mfma_f32_32x32x16_bf16 v[2:17], v[236:239], v[146:149], 0
	v_mfma_f32_32x32x16_bf16 v[34:49], v[240:243], v[134:137], v[34:49]
	v_mfma_f32_32x32x16_bf16 v[2:17], v[240:243], v[150:153], v[2:17]
	v_mfma_f32_32x32x16_bf16 v[34:49], v[244:247], v[138:141], v[34:49]
	v_mfma_f32_32x32x16_bf16 v[2:17], v[244:247], v[154:157], v[2:17]
	v_mfma_f32_32x32x16_bf16 v[34:49], v[248:251], v[142:145], v[34:49]
	v_mfma_f32_32x32x16_bf16 v[2:17], v[248:251], v[158:161], v[2:17]
	s_setprio 0
	s_barrier
	ds_read_b128 v[196:199], v203 offset:32768
	ds_read_b128 v[208:211], v204 offset:32768
	ds_read_b128 v[218:221], v214 offset:32768
	ds_read_b128 v[222:225], v226 offset:32768
	ds_read_b128 v[130:133], v192 offset:32768
	ds_read_b128 v[134:137], v193 offset:32768
	ds_read_b128 v[138:141], v194 offset:32768
	ds_read_b128 v[142:145], v195 offset:32768
	ds_read_b128 v[146:149], v192 offset:36864
	ds_read_b128 v[150:153], v193 offset:36864
	ds_read_b128 v[154:157], v194 offset:36864
	ds_read_b128 v[158:161], v195 offset:36864
	s_add_u32 m0, s16, 0x2000
	s_nop 0
	global_load_lds_dwordx4 v227, s[12:13]
	s_add_u32 m0, s16, 0x2400
	s_nop 0
	global_load_lds_dwordx4 v228, s[12:13]
	s_add_u32 s12, s12, 0x80
	s_addc_u32 s13, s13, 0
	s_waitcnt lgkmcnt(8)
	s_barrier
	s_waitcnt lgkmcnt(0)
	s_setprio 1
	v_mfma_f32_32x32x16_bf16 v[114:129], v[196:199], v[130:133], v[114:129]
	v_mfma_f32_32x32x16_bf16 v[82:97], v[196:199], v[146:149], v[82:97]
	v_mfma_f32_32x32x16_bf16 v[114:129], v[208:211], v[134:137], v[114:129]
	v_mfma_f32_32x32x16_bf16 v[82:97], v[208:211], v[150:153], v[82:97]
	v_mfma_f32_32x32x16_bf16 v[114:129], v[218:221], v[138:141], v[114:129]
	v_mfma_f32_32x32x16_bf16 v[82:97], v[218:221], v[154:157], v[82:97]
	v_mfma_f32_32x32x16_bf16 v[114:129], v[222:225], v[142:145], v[114:129]
	v_mfma_f32_32x32x16_bf16 v[82:97], v[222:225], v[158:161], v[82:97]
	s_setprio 0
	s_barrier
	ds_read_b128 v[236:239], v203 offset:36864
	ds_read_b128 v[240:243], v204 offset:36864
	ds_read_b128 v[244:247], v214 offset:36864
	ds_read_b128 v[248:251], v226 offset:36864
	s_add_u32 m0, s40, 0x8000
	s_nop 0
	global_load_lds_dwordx4 v227, s[14:15]
	s_add_u32 m0, s40, 0x8400
	s_nop 0
	global_load_lds_dwordx4 v228, s[14:15]
	s_add_u32 s14, s14, 0x80
	s_addc_u32 s15, s15, 0
	s_barrier
	s_waitcnt lgkmcnt(0)
	s_setprio 1
	v_mfma_f32_32x32x16_bf16 v[98:113], v[236:239], v[130:133], v[98:113]
	v_mfma_f32_32x32x16_bf16 v[66:81], v[236:239], v[146:149], v[66:81]
	v_mfma_f32_32x32x16_bf16 v[98:113], v[240:243], v[134:137], v[98:113]
	v_mfma_f32_32x32x16_bf16 v[66:81], v[240:243], v[150:153], v[66:81]
	v_mfma_f32_32x32x16_bf16 v[98:113], v[244:247], v[138:141], v[98:113]
	v_mfma_f32_32x32x16_bf16 v[66:81], v[244:247], v[154:157], v[66:81]
	v_mfma_f32_32x32x16_bf16 v[98:113], v[248:251], v[142:145], v[98:113]
	v_mfma_f32_32x32x16_bf16 v[66:81], v[248:251], v[158:161], v[66:81]
	s_setprio 0
	s_barrier
	ds_read_b128 v[130:133], v192 offset:40960
	ds_read_b128 v[134:137], v193 offset:40960
	ds_read_b128 v[138:141], v194 offset:40960
	ds_read_b128 v[142:145], v195 offset:40960
	ds_read_b128 v[146:149], v192 offset:45056
	ds_read_b128 v[150:153], v193 offset:45056
	ds_read_b128 v[154:157], v194 offset:45056
	ds_read_b128 v[158:161], v195 offset:45056
	s_add_u32 m0, s16, 0x8000
	s_nop 0
	global_load_lds_dwordx4 v227, s[2:3]
	s_add_u32 m0, s16, 0x8400
	s_nop 0
	global_load_lds_dwordx4 v228, s[2:3]
	s_add_u32 s2, s2, 0x80
	s_addc_u32 s3, s3, 0
	s_barrier
	s_waitcnt lgkmcnt(0)
	s_setprio 1
	v_mfma_f32_32x32x16_bf16 v[50:65], v[196:199], v[130:133], v[50:65]
	v_mfma_f32_32x32x16_bf16 v[18:33], v[196:199], v[146:149], v[18:33]
	v_mfma_f32_32x32x16_bf16 v[50:65], v[208:211], v[134:137], v[50:65]
	v_mfma_f32_32x32x16_bf16 v[18:33], v[208:211], v[150:153], v[18:33]
	v_mfma_f32_32x32x16_bf16 v[50:65], v[218:221], v[138:141], v[50:65]
	v_mfma_f32_32x32x16_bf16 v[18:33], v[218:221], v[154:157], v[18:33]
	v_mfma_f32_32x32x16_bf16 v[50:65], v[222:225], v[142:145], v[50:65]
	v_mfma_f32_32x32x16_bf16 v[18:33], v[222:225], v[158:161], v[18:33]
	s_setprio 0
	s_barrier
	s_add_u32 m0, s40, 0x9000
	s_nop 0
	global_load_lds_dwordx4 v227, s[22:23]
	s_add_u32 m0, s40, 0x9400
	s_nop 0
	global_load_lds_dwordx4 v228, s[22:23]
	s_add_u32 s22, s22, 0x80
	s_addc_u32 s23, s23, 0
	s_waitcnt vmcnt(6)
	s_barrier
	s_setprio 1
	v_mfma_f32_32x32x16_bf16 v[34:49], v[236:239], v[130:133], v[34:49]
	v_mfma_f32_32x32x16_bf16 v[2:17], v[236:239], v[146:149], v[2:17]
	v_mfma_f32_32x32x16_bf16 v[34:49], v[240:243], v[134:137], v[34:49]
	v_mfma_f32_32x32x16_bf16 v[2:17], v[240:243], v[150:153], v[2:17]
	v_mfma_f32_32x32x16_bf16 v[34:49], v[244:247], v[138:141], v[34:49]
	v_mfma_f32_32x32x16_bf16 v[2:17], v[244:247], v[154:157], v[2:17]
	v_mfma_f32_32x32x16_bf16 v[34:49], v[248:251], v[142:145], v[34:49]
	v_mfma_f32_32x32x16_bf16 v[2:17], v[248:251], v[158:161], v[2:17]
	s_setprio 0
	s_barrier
	s_mov_b32 s41, 2
